# w_down f32->bf16 transposes (1024 tiles) moved from phase 0 to the end of phase 2, executed by workgroups 32-255 that otherwise idle at the grid barrier while workgroups 0-31 run the FoX cumsum round
# speedup vs baseline: 1.0045x; 1.0045x over previous
; __global__ void __launch_bounds__(512, 2) fwd_mega(Params P) {
;     ...
;     {
;     for (int base = bid * 2; base < 1984 + 4096; base += nblk * 2) {
;         PHASE_IDS
;         const int it = base + team;
;         if (it < 960) {
;             transpose_tile(P.in[4], 1024, 3600, (bf16_t*)(ws + OFF_WIN), it / 60, it % 60, 1, (float*)smem, tt);
;         } else if (it < 1984) {
;             const int loc = it - 960;
;             transpose_tile(P.in[15], 4096, 1024, (bf16_t*)(ws + OFF_WDOWN), loc / 16, loc % 16, 0, (float*)smem, tt);
.LBB0_17:
	v_writelane_b32 v255, s12, 19
	s_load_dwordx16 s[44:59], s[0:1], 0x40
	s_lshl_b32 s86, s33, 1
	s_waitcnt lgkmcnt(0)
	v_writelane_b32 v255, s58, 60
	v_writelane_b32 v255, s59, 61
	v_writelane_b32 v255, s13, 20
	v_writelane_b32 v255, s14, 21
	v_writelane_b32 v255, s15, 22
	v_writelane_b32 v255, s16, 23
	v_writelane_b32 v255, s17, 24
	v_writelane_b32 v255, s18, 25
	v_writelane_b32 v255, s19, 26
	s_cmpk_gt_i32 s33, 0xbdf
	s_cbranch_scc1 .LBB0_40
	s_and_b32 s16, s96, 0xffffffc0
	s_add_u32 s0, s80, 0x9000000
	s_addc_u32 s1, s81, 0
	s_add_u32 s2, s80, 0x1c80000
	s_addc_u32 s3, s81, 0
	s_add_u32 s4, s80, 0xf800000
	s_addc_u32 s5, s81, 0
	s_add_u32 s6, s80, 0x1200000
	s_addc_u32 s7, s81, 0
	s_lshl_b32 s17, s82, 1
	s_mov_b32 s18, 0x12c00
	s_movk_i32 s19, 0x3bf
	s_movk_i32 s20, 0x7bf
	v_mov_b32_e32 v17, 0
	v_mov_b32_e32 v18, 0x3727c5ac
	s_mov_b32 s21, 0x800000
	s_movk_i32 s22, 0xfc
	s_mov_b32 s23, 0x88888889
	s_movk_i32 s24, 0x7ff
	s_movk_i32 s25, 0xdff
	s_movk_i32 s26, 0xe07
	s_movk_i32 s27, 0xe10
	s_movk_i32 s28, 0x3840
	v_mov_b32_e32 v19, 2
	v_mov_b32_e32 v20, 4
	s_mov_b32 s29, s86
	s_branch .LBB0_22

; __global__ void __launch_bounds__(512, 2) fwd_mega(Params P) {
;     ...
;     for (int base = bid * 2; base < 1984 + 4096; base += nblk * 2) {
;         PHASE_IDS
;         const int it = base + team;
;         if (it < 960) {
;             transpose_tile(P.in[4], 1024, 3600, (bf16_t*)(ws + OFF_WIN), it / 60, it % 60, 1, (float*)smem, tt);
;         } else if (it < 1984) {
;             const int loc = it - 960;
;             transpose_tile(P.in[15], 4096, 1024, (bf16_t*)(ws + OFF_WDOWN), loc / 16, loc % 16, 0, (float*)smem, tt);
.LBB0_21:
	s_or_b64 exec, exec, s[8:9]
	s_add_i32 s29, s29, s17
	s_cmpk_gt_i32 s29, 0x13bf
	s_cbranch_scc1 .LBB0_40
.LBB0_22:
	v_mbcnt_lo_u32_b32 v1, -1, 0
	v_mbcnt_hi_u32_b32 v1, -1, v1
	s_nop 0
	v_add_u32_e32 v0, s16, v1
	v_ashrrev_i32_e32 v3, 8, v0
	v_and_b32_e32 v21, 63, v1
	v_mad_i32_i24 v1, v3, s18, 0
	v_add_u32_e32 v3, s29, v3
	v_cmp_lt_i32_e32 vcc, s19, v3
	s_and_saveexec_b64 s[100:101], vcc
	v_add_u32_e32 v3, 0x400, v3
	s_mov_b64 exec, s[100:101]
	v_bfe_u32 v2, v0, 6, 2
	v_cmp_lt_i32_e32 vcc, s19, v3
	s_and_saveexec_b64 s[8:9], vcc
	s_xor_b64 s[8:9], exec, s[8:9]
	s_cbranch_execnz .LBB0_24
	s_andn2_saveexec_b64 s[8:9], s[8:9]
	s_cbranch_execz .LBB0_21
	s_branch .LBB0_31

; DI unsigned pack2(float lo, float hi) { f32x2_t v = {lo, hi}; bf16x2_t b = __builtin_convertvector(v, bf16x2_t); return __builtin_bit_cast(unsigned, b); }
; DI void transpose_tile(const float* __restrict__ W, int K, int N, bf16_t* __restrict__ Wt, int kt, int nt, int mode, float* tile, int tt) {
;     const int tid = tt;
;     const int k0 = kt * 64, n0 = nt * 64;
;     {
;         const int c = tid & 63, n = n0 + c;
;         int sc = n;
;         if (mode == 1) { sc = (n < 2048) ? n : (n < 3584) ? n + 8 : (n < 3592) ? 2048 + (n - 3584) : (n < 3600) ? n : -1; }
;         const int scc = sc >= 0 ? sc : 0;
;         const float mk = sc >= 0 ? 1.f : 0.f;
;         float wv[16];
; #pragma unroll
;         for (int i = 0; i < 16; ++i) wv[i] = W[(size_t)(k0 + (tid >> 6) + 4 * i) * N + scc];
; #pragma unroll
;         for (int i = 0; i < 16; ++i) tile[((tid >> 6) + 4 * i) * 65 + c] = wv[i] * mk;
;     }
;     __syncthreads();
;     {
;         const int n = tid >> 2, ks = (tid & 3) * 16;
;         u32x4 o0, o1;
;         o0.x = pack2(tile[(ks + 0) * 65 + n], tile[(ks + 1) * 65 + n]); o0.y = pack2(tile[(ks + 2) * 65 + n], tile[(ks + 3) * 65 + n]);
;         o0.z = pack2(tile[(ks + 4) * 65 + n], tile[(ks + 5) * 65 + n]); o0.w = pack2(tile[(ks + 6) * 65 + n], tile[(ks + 7) * 65 + n]);
;         o1.x = pack2(tile[(ks + 8) * 65 + n], tile[(ks + 9) * 65 + n]); o1.y = pack2(tile[(ks + 10) * 65 + n], tile[(ks + 11) * 65 + n]);
;         o1.z = pack2(tile[(ks + 12) * 65 + n], tile[(ks + 13) * 65 + n]); o1.w = pack2(tile[(ks + 14) * 65 + n], tile[(ks + 15) * 65 + n]);
;         bf16_t* dst = Wt + (size_t)(n0 + n) * K + k0 + ks;
;         *(u32x4*)dst = o0; *(u32x4*)(dst + 8) = o1;
;     }
;     __syncthreads();
.LBB0_477:
	s_cmp_lt_u32 s33, 32
	s_cbranch_scc1 .Lwd_done
	v_mbcnt_lo_u32_b32 v100, -1, 0
	v_mbcnt_hi_u32_b32 v100, -1, v100
	v_readlane_b32 s98, v255, 39
	v_readlane_b32 s60, v255, 60
	v_readlane_b32 s61, v255, 61
	s_sub_u32 s99, s33, 32
	s_lshl_b32 s99, s99, 1
	s_add_u32 s62, s80, 0x1200000
	s_addc_u32 s63, s81, 0
	s_mov_b64 s[64:65], 0x4000
	v_add_u32_e32 v101, s98, v100
	v_lshrrev_b32_e32 v102, 8, v101
	v_and_b32_e32 v103, 0xff, v101
	v_and_b32_e32 v104, 63, v103
	v_lshrrev_b32_e32 v105, 6, v103
	v_lshrrev_b32_e32 v106, 2, v103
	v_and_b32_e32 v107, 3, v103
	v_mul_u32_u24_e32 v108, 0x12c00, v102
	v_mul_u32_u24_e32 v109, 65, v105
	v_add_lshl_u32 v109, v109, v104, 2
	v_add_u32_e32 v109, v108, v109
	v_mul_u32_u24_e32 v110, 0x410, v107
	v_add_lshl_u32 v110, v110, v106, 2
	v_add_u32_e32 v110, v108, v110
.Lwd_loop:
	s_cmp_ge_u32 s99, 0x400
	s_cbranch_scc1 .Lwd_done
	v_add_u32_e32 v111, s99, v102
	v_lshrrev_b32_e32 v112, 4, v111
	v_and_b32_e32 v113, 15, v111
	v_lshl_add_u32 v114, v112, 6, v105
	v_lshlrev_b32_e32 v114, 10, v114
	v_lshl_add_u32 v115, v113, 6, v104
	v_add_u32_e32 v114, v114, v115
	v_mov_b32_e32 v115, 0
	v_lshl_add_u64 v[116:117], v[114:115], 2, s[60:61]
	global_load_dword v120, v[116:117], off
	v_lshl_add_u64 v[116:117], v[116:117], 0, s[64:65]
	global_load_dword v121, v[116:117], off
	v_lshl_add_u64 v[116:117], v[116:117], 0, s[64:65]
	global_load_dword v122, v[116:117], off
	v_lshl_add_u64 v[116:117], v[116:117], 0, s[64:65]
	global_load_dword v123, v[116:117], off
	v_lshl_add_u64 v[116:117], v[116:117], 0, s[64:65]
	global_load_dword v124, v[116:117], off
	v_lshl_add_u64 v[116:117], v[116:117], 0, s[64:65]
	global_load_dword v125, v[116:117], off
	v_lshl_add_u64 v[116:117], v[116:117], 0, s[64:65]
	global_load_dword v126, v[116:117], off
	v_lshl_add_u64 v[116:117], v[116:117], 0, s[64:65]
	global_load_dword v127, v[116:117], off
	v_lshl_add_u64 v[116:117], v[116:117], 0, s[64:65]
	global_load_dword v128, v[116:117], off
	v_lshl_add_u64 v[116:117], v[116:117], 0, s[64:65]
	global_load_dword v129, v[116:117], off
	v_lshl_add_u64 v[116:117], v[116:117], 0, s[64:65]
	global_load_dword v130, v[116:117], off
	v_lshl_add_u64 v[116:117], v[116:117], 0, s[64:65]
	global_load_dword v131, v[116:117], off
	v_lshl_add_u64 v[116:117], v[116:117], 0, s[64:65]
	global_load_dword v132, v[116:117], off
	v_lshl_add_u64 v[116:117], v[116:117], 0, s[64:65]
	global_load_dword v133, v[116:117], off
	v_lshl_add_u64 v[116:117], v[116:117], 0, s[64:65]
	global_load_dword v134, v[116:117], off
	v_lshl_add_u64 v[116:117], v[116:117], 0, s[64:65]
	global_load_dword v135, v[116:117], off
	s_waitcnt vmcnt(15)
	ds_write_b32 v109, v120
	s_waitcnt vmcnt(14)
	ds_write_b32 v109, v121 offset:1040
	s_waitcnt vmcnt(13)
	ds_write_b32 v109, v122 offset:2080
	s_waitcnt vmcnt(12)
	ds_write_b32 v109, v123 offset:3120
	s_waitcnt vmcnt(11)
	ds_write_b32 v109, v124 offset:4160
	s_waitcnt vmcnt(10)
	ds_write_b32 v109, v125 offset:5200
	s_waitcnt vmcnt(9)
	ds_write_b32 v109, v126 offset:6240
	s_waitcnt vmcnt(8)
	ds_write_b32 v109, v127 offset:7280
	s_waitcnt vmcnt(7)
	ds_write_b32 v109, v128 offset:8320
	s_waitcnt vmcnt(6)
	ds_write_b32 v109, v129 offset:9360
	s_waitcnt vmcnt(5)
	ds_write_b32 v109, v130 offset:10400
	s_waitcnt vmcnt(4)
	ds_write_b32 v109, v131 offset:11440
	s_waitcnt vmcnt(3)
	ds_write_b32 v109, v132 offset:12480
	s_waitcnt vmcnt(2)
	ds_write_b32 v109, v133 offset:13520
	s_waitcnt vmcnt(1)
	ds_write_b32 v109, v134 offset:14560
	s_waitcnt vmcnt(0)
	ds_write_b32 v109, v135 offset:15600
	s_waitcnt lgkmcnt(0)
	s_barrier
	ds_read_b32 v136, v110
	ds_read_b32 v137, v110 offset:260
	ds_read_b32 v138, v110 offset:520
	ds_read_b32 v139, v110 offset:780
	ds_read_b32 v140, v110 offset:1040
	ds_read_b32 v141, v110 offset:1300
	ds_read_b32 v142, v110 offset:1560
	ds_read_b32 v143, v110 offset:1820
	ds_read_b32 v144, v110 offset:2080
	ds_read_b32 v145, v110 offset:2340
	ds_read_b32 v146, v110 offset:2600
	ds_read_b32 v147, v110 offset:2860
	ds_read_b32 v148, v110 offset:3120
	ds_read_b32 v149, v110 offset:3380
	ds_read_b32 v150, v110 offset:3640
	ds_read_b32 v151, v110 offset:3900
	v_lshl_add_u32 v118, v113, 6, v106
	v_lshlrev_b32_e32 v118, 12, v118
	v_lshlrev_b32_e32 v119, 4, v107
	v_lshl_add_u32 v119, v112, 6, v119
	v_add_u32_e32 v160, v118, v119
	v_mov_b32_e32 v161, 0
	v_lshl_add_u64 v[162:163], v[160:161], 1, s[62:63]
	s_waitcnt lgkmcnt(0)
	s_barrier
	v_cvt_pk_bf16_f32 v152, v136, v137
	v_cvt_pk_bf16_f32 v153, v138, v139
	v_cvt_pk_bf16_f32 v154, v140, v141
	v_cvt_pk_bf16_f32 v155, v142, v143
	v_cvt_pk_bf16_f32 v156, v144, v145
	v_cvt_pk_bf16_f32 v157, v146, v147
	v_cvt_pk_bf16_f32 v158, v148, v149
	v_cvt_pk_bf16_f32 v159, v150, v151
	global_store_dwordx4 v[162:163], v[152:155], off
	global_store_dwordx4 v[162:163], v[156:159], off offset:16
	s_addk_i32 s99, 0x1c0
	s_branch .Lwd_loop
